# EpiAct stores: lanes transposed with ds_bpermute so consecutive lanes write consecutive bytes (32 B per row per 4 lanes)
# baseline (speedup 1.0000x reference)
.LBB0_961:
	s_ashr_i32 s27, s26, 31
	s_lshl_b64 s[26:27], s[26:27], 19
	s_add_u32 s21, s57, s26
	s_addc_u32 s30, s58, s27
	s_ashr_i32 s29, s28, 31
	s_lshl_b64 s[26:27], s[28:29], 7
	s_add_u32 s21, s21, s26
	s_addc_u32 s27, s30, s27
	s_add_u32 s26, s21, s59
	s_addc_u32 s27, s27, 0
	s_mov_b32 s98, 0x44800000
	s_mov_b32 s99, 0x44800000
	v_pk_mul_f32 v[64:65], v[120:121], s[10:11] op_sel_hi:[1,0]
	v_pk_mul_f32 v[66:67], v[122:123], s[10:11] op_sel_hi:[1,0]
	v_pk_mul_f32 v[68:69], v[112:113], s[10:11] op_sel_hi:[1,0]
	v_pk_mul_f32 v[70:71], v[114:115], s[10:11] op_sel_hi:[1,0]
	v_exp_f32_e32 v64, v64
	v_exp_f32_e32 v65, v65
	v_exp_f32_e32 v66, v66
	v_exp_f32_e32 v67, v67
	v_exp_f32_e32 v68, v68
	v_exp_f32_e32 v69, v69
	v_exp_f32_e32 v70, v70
	v_exp_f32_e32 v71, v71
	v_pk_fma_f32 v[64:65], v[64:65], s[98:99], s[98:99]
	v_pk_fma_f32 v[66:67], v[66:67], s[98:99], s[98:99]
	v_pk_fma_f32 v[68:69], v[68:69], s[98:99], s[98:99]
	v_pk_fma_f32 v[70:71], v[70:71], s[98:99], s[98:99]
	v_rcp_f32_e32 v64, v64
	v_rcp_f32_e32 v65, v65
	v_pk_mul_f32 v[120:121], v[120:121], v[124:125]
	v_rcp_f32_e32 v66, v66
	v_rcp_f32_e32 v67, v67
	v_pk_mul_f32 v[122:123], v[122:123], v[126:127]
	v_rcp_f32_e32 v68, v68
	v_rcp_f32_e32 v69, v69
	v_pk_mul_f32 v[112:113], v[112:113], v[116:117]
	v_rcp_f32_e32 v70, v70
	v_rcp_f32_e32 v71, v71
	v_pk_mul_f32 v[114:115], v[114:115], v[118:119]
	v_mbcnt_lo_u32_b32 v136, -1, 0
	v_mbcnt_hi_u32_b32 v136, -1, v136
	v_lshrrev_b32_e32 v137, 2, v136
	v_and_b32_e32 v124, 15, v136
	v_sub_u32_e32 v124, v137, v124
	v_lshlrev_b32_e32 v124, 11, v124
	v_and_b32_e32 v136, 3, v136
	v_lshl_add_u32 v124, v136, 3, v124
	v_add_u32_e32 v124, v134, v124
	v_lshl_add_u32 v125, v136, 4, v137
	v_lshlrev_b32_e32 v125, 2, v125
	v_pk_mul_f32 v[120:121], v[120:121], v[64:65]
	v_pk_mul_f32 v[122:123], v[122:123], v[66:67]
	v_pk_mul_f32 v[112:113], v[112:113], v[68:69]
	v_pk_mul_f32 v[114:115], v[114:115], v[70:71]
	v_med3_f32 v120, v120, s68, v150
	v_med3_f32 v121, v121, s68, v150
	v_med3_f32 v122, v122, s68, v150
	v_med3_f32 v123, v123, s68, v150
	v_med3_f32 v112, v112, s68, v150
	v_med3_f32 v113, v113, s68, v150
	v_med3_f32 v114, v114, s68, v150
	v_med3_f32 v115, v115, s68, v150
	v_cvt_pk_fp8_f32 v136, v120, v121
	v_cvt_pk_fp8_f32 v137, v112, v113
	v_cvt_pk_fp8_f32 v136, v122, v123 op_sel:[0,0,1]
	v_cvt_pk_fp8_f32 v137, v114, v115 op_sel:[0,0,1]
	s_nop 0
	ds_bpermute_b32 v126, v125, v136
	ds_bpermute_b32 v127, v125, v137
	v_pk_mul_f32 v[64:65], v[104:105], s[10:11] op_sel_hi:[1,0]
	v_pk_mul_f32 v[66:67], v[106:107], s[10:11] op_sel_hi:[1,0]
	v_pk_mul_f32 v[68:69], v[96:97], s[10:11] op_sel_hi:[1,0]
	v_pk_mul_f32 v[70:71], v[98:99], s[10:11] op_sel_hi:[1,0]
	v_exp_f32_e32 v64, v64
	v_exp_f32_e32 v65, v65
	v_exp_f32_e32 v66, v66
	v_exp_f32_e32 v67, v67
	v_exp_f32_e32 v68, v68
	v_exp_f32_e32 v69, v69
	v_exp_f32_e32 v70, v70
	v_exp_f32_e32 v71, v71
	v_pk_fma_f32 v[64:65], v[64:65], s[98:99], s[98:99]
	v_pk_fma_f32 v[66:67], v[66:67], s[98:99], s[98:99]
	v_pk_fma_f32 v[68:69], v[68:69], s[98:99], s[98:99]
	v_pk_fma_f32 v[70:71], v[70:71], s[98:99], s[98:99]
	v_rcp_f32_e32 v64, v64
	v_rcp_f32_e32 v65, v65
	v_pk_mul_f32 v[104:105], v[104:105], v[108:109]
	v_rcp_f32_e32 v66, v66
	v_rcp_f32_e32 v67, v67
	v_pk_mul_f32 v[106:107], v[106:107], v[110:111]
	v_rcp_f32_e32 v68, v68
	v_rcp_f32_e32 v69, v69
	v_pk_mul_f32 v[96:97], v[96:97], v[100:101]
	v_rcp_f32_e32 v70, v70
	v_rcp_f32_e32 v71, v71
	v_pk_mul_f32 v[98:99], v[98:99], v[102:103]
	v_pk_mul_f32 v[104:105], v[104:105], v[64:65]
	v_pk_mul_f32 v[106:107], v[106:107], v[66:67]
	v_pk_mul_f32 v[96:97], v[96:97], v[68:69]
	v_pk_mul_f32 v[98:99], v[98:99], v[70:71]
	v_med3_f32 v104, v104, s68, v150
	v_med3_f32 v105, v105, s68, v150
	v_med3_f32 v106, v106, s68, v150
	v_med3_f32 v107, v107, s68, v150
	v_med3_f32 v96, v96, s68, v150
	v_med3_f32 v97, v97, s68, v150
	v_med3_f32 v98, v98, s68, v150
	v_med3_f32 v99, v99, s68, v150
	v_cvt_pk_fp8_f32 v140, v104, v105
	v_cvt_pk_fp8_f32 v141, v96, v97
	v_cvt_pk_fp8_f32 v140, v106, v107 op_sel:[0,0,1]
	v_cvt_pk_fp8_f32 v141, v98, v99 op_sel:[0,0,1]
	s_nop 0
	ds_bpermute_b32 v118, v125, v140
	ds_bpermute_b32 v119, v125, v141
	s_waitcnt lgkmcnt(2)
	s_mov_b32 s100, s26
	s_mov_b32 s101, s27
	global_store_dwordx2 v124, v[126:127], s[100:101]
	v_pk_mul_f32 v[64:65], v[88:89], s[10:11] op_sel_hi:[1,0]
	v_pk_mul_f32 v[66:67], v[90:91], s[10:11] op_sel_hi:[1,0]
	v_pk_mul_f32 v[68:69], v[80:81], s[10:11] op_sel_hi:[1,0]
	v_pk_mul_f32 v[70:71], v[82:83], s[10:11] op_sel_hi:[1,0]
	v_exp_f32_e32 v64, v64
	v_exp_f32_e32 v65, v65
	v_exp_f32_e32 v66, v66
	v_exp_f32_e32 v67, v67
	v_exp_f32_e32 v68, v68
	v_exp_f32_e32 v69, v69
	v_exp_f32_e32 v70, v70
	v_exp_f32_e32 v71, v71
	v_pk_fma_f32 v[64:65], v[64:65], s[98:99], s[98:99]
	v_pk_fma_f32 v[66:67], v[66:67], s[98:99], s[98:99]
	v_pk_fma_f32 v[68:69], v[68:69], s[98:99], s[98:99]
	v_pk_fma_f32 v[70:71], v[70:71], s[98:99], s[98:99]
	v_rcp_f32_e32 v64, v64
	v_rcp_f32_e32 v65, v65
	v_pk_mul_f32 v[88:89], v[88:89], v[92:93]
	v_rcp_f32_e32 v66, v66
	v_rcp_f32_e32 v67, v67
	v_pk_mul_f32 v[90:91], v[90:91], v[94:95]
	v_rcp_f32_e32 v68, v68
	v_rcp_f32_e32 v69, v69
	v_pk_mul_f32 v[80:81], v[80:81], v[84:85]
	v_rcp_f32_e32 v70, v70
	v_rcp_f32_e32 v71, v71
	v_pk_mul_f32 v[82:83], v[82:83], v[86:87]
	v_pk_mul_f32 v[88:89], v[88:89], v[64:65]
	v_pk_mul_f32 v[90:91], v[90:91], v[66:67]
	v_pk_mul_f32 v[80:81], v[80:81], v[68:69]
	v_pk_mul_f32 v[82:83], v[82:83], v[70:71]
	v_med3_f32 v88, v88, s68, v150
	v_med3_f32 v89, v89, s68, v150
	v_med3_f32 v90, v90, s68, v150
	v_med3_f32 v91, v91, s68, v150
	v_med3_f32 v80, v80, s68, v150
	v_med3_f32 v81, v81, s68, v150
	v_med3_f32 v82, v82, s68, v150
	v_med3_f32 v83, v83, s68, v150
	v_cvt_pk_fp8_f32 v136, v88, v89
	v_cvt_pk_fp8_f32 v137, v80, v81
	v_cvt_pk_fp8_f32 v136, v90, v91 op_sel:[0,0,1]
	v_cvt_pk_fp8_f32 v137, v82, v83 op_sel:[0,0,1]
	s_nop 0
	ds_bpermute_b32 v126, v125, v136
	ds_bpermute_b32 v127, v125, v137
	s_waitcnt lgkmcnt(2)
	s_add_u32 s100, s26, 0x8000
	s_addc_u32 s101, s27, 0
	global_store_dwordx2 v124, v[118:119], s[100:101]
	v_pk_mul_f32 v[64:65], v[72:73], s[10:11] op_sel_hi:[1,0]
	v_pk_mul_f32 v[66:67], v[74:75], s[10:11] op_sel_hi:[1,0]
	v_pk_mul_f32 v[68:69], v[230:231], s[10:11] op_sel_hi:[1,0]
	v_pk_mul_f32 v[70:71], v[232:233], s[10:11] op_sel_hi:[1,0]
	v_exp_f32_e32 v64, v64
	v_exp_f32_e32 v65, v65
	v_exp_f32_e32 v66, v66
	v_exp_f32_e32 v67, v67
	v_exp_f32_e32 v68, v68
	v_exp_f32_e32 v69, v69
	v_exp_f32_e32 v70, v70
	v_exp_f32_e32 v71, v71
	v_pk_fma_f32 v[64:65], v[64:65], s[98:99], s[98:99]
	v_pk_fma_f32 v[66:67], v[66:67], s[98:99], s[98:99]
	v_pk_fma_f32 v[68:69], v[68:69], s[98:99], s[98:99]
	v_pk_fma_f32 v[70:71], v[70:71], s[98:99], s[98:99]
	v_rcp_f32_e32 v64, v64
	v_rcp_f32_e32 v65, v65
	v_pk_mul_f32 v[72:73], v[72:73], v[76:77]
	v_rcp_f32_e32 v66, v66
	v_rcp_f32_e32 v67, v67
	v_pk_mul_f32 v[74:75], v[74:75], v[78:79]
	v_rcp_f32_e32 v68, v68
	v_rcp_f32_e32 v69, v69
	v_pk_mul_f32 v[230:231], v[230:231], v[20:21]
	v_rcp_f32_e32 v70, v70
	v_rcp_f32_e32 v71, v71
	v_pk_mul_f32 v[232:233], v[232:233], v[22:23]
	v_pk_mul_f32 v[72:73], v[72:73], v[64:65]
	v_pk_mul_f32 v[74:75], v[74:75], v[66:67]
	v_pk_mul_f32 v[230:231], v[230:231], v[68:69]
	v_pk_mul_f32 v[232:233], v[232:233], v[70:71]
	v_med3_f32 v72, v72, s68, v150
	v_med3_f32 v73, v73, s68, v150
	v_med3_f32 v74, v74, s68, v150
	v_med3_f32 v75, v75, s68, v150
	v_med3_f32 v230, v230, s68, v150
	v_med3_f32 v231, v231, s68, v150
	v_med3_f32 v232, v232, s68, v150
	v_med3_f32 v233, v233, s68, v150
	v_cvt_pk_fp8_f32 v140, v72, v73
	v_cvt_pk_fp8_f32 v141, v230, v231
	v_cvt_pk_fp8_f32 v140, v74, v75 op_sel:[0,0,1]
	v_cvt_pk_fp8_f32 v141, v232, v233 op_sel:[0,0,1]
	s_nop 0
	ds_bpermute_b32 v118, v125, v140
	ds_bpermute_b32 v119, v125, v141
	s_waitcnt lgkmcnt(2)
	s_add_u32 s100, s26, 0x10000
	s_addc_u32 s101, s27, 0
	global_store_dwordx2 v124, v[126:127], s[100:101]
	v_pk_mul_f32 v[64:65], v[56:57], s[10:11] op_sel_hi:[1,0]
	v_pk_mul_f32 v[66:67], v[58:59], s[10:11] op_sel_hi:[1,0]
	v_pk_mul_f32 v[68:69], v[48:49], s[10:11] op_sel_hi:[1,0]
	v_pk_mul_f32 v[70:71], v[50:51], s[10:11] op_sel_hi:[1,0]
	v_exp_f32_e32 v64, v64
	v_exp_f32_e32 v65, v65
	v_exp_f32_e32 v66, v66
	v_exp_f32_e32 v67, v67
	v_exp_f32_e32 v68, v68
	v_exp_f32_e32 v69, v69
	v_exp_f32_e32 v70, v70
	v_exp_f32_e32 v71, v71
	v_pk_fma_f32 v[64:65], v[64:65], s[98:99], s[98:99]
	v_pk_fma_f32 v[66:67], v[66:67], s[98:99], s[98:99]
	v_pk_fma_f32 v[68:69], v[68:69], s[98:99], s[98:99]
	v_pk_fma_f32 v[70:71], v[70:71], s[98:99], s[98:99]
	v_rcp_f32_e32 v64, v64
	v_rcp_f32_e32 v65, v65
	v_pk_mul_f32 v[56:57], v[56:57], v[60:61]
	v_rcp_f32_e32 v66, v66
	v_rcp_f32_e32 v67, v67
	v_pk_mul_f32 v[58:59], v[58:59], v[62:63]
	v_rcp_f32_e32 v68, v68
	v_rcp_f32_e32 v69, v69
	v_pk_mul_f32 v[48:49], v[48:49], v[52:53]
	v_rcp_f32_e32 v70, v70
	v_rcp_f32_e32 v71, v71
	v_pk_mul_f32 v[50:51], v[50:51], v[54:55]
	v_pk_mul_f32 v[56:57], v[56:57], v[64:65]
	v_pk_mul_f32 v[58:59], v[58:59], v[66:67]
	v_pk_mul_f32 v[48:49], v[48:49], v[68:69]
	v_pk_mul_f32 v[50:51], v[50:51], v[70:71]
	v_med3_f32 v56, v56, s68, v150
	v_med3_f32 v57, v57, s68, v150
	v_med3_f32 v58, v58, s68, v150
	v_med3_f32 v59, v59, s68, v150
	v_med3_f32 v48, v48, s68, v150
	v_med3_f32 v49, v49, s68, v150
	v_med3_f32 v50, v50, s68, v150
	v_med3_f32 v51, v51, s68, v150
	v_cvt_pk_fp8_f32 v136, v56, v57
	v_cvt_pk_fp8_f32 v137, v48, v49
	v_cvt_pk_fp8_f32 v136, v58, v59 op_sel:[0,0,1]
	v_cvt_pk_fp8_f32 v137, v50, v51 op_sel:[0,0,1]
	s_nop 0
	ds_bpermute_b32 v126, v125, v136
	ds_bpermute_b32 v127, v125, v137
	s_waitcnt lgkmcnt(2)
	s_add_u32 s100, s26, 0x18000
	s_addc_u32 s101, s27, 0
	global_store_dwordx2 v124, v[118:119], s[100:101]
	v_pk_mul_f32 v[64:65], v[40:41], s[10:11] op_sel_hi:[1,0]
	v_pk_mul_f32 v[66:67], v[42:43], s[10:11] op_sel_hi:[1,0]
	v_pk_mul_f32 v[68:69], v[32:33], s[10:11] op_sel_hi:[1,0]
	v_pk_mul_f32 v[70:71], v[34:35], s[10:11] op_sel_hi:[1,0]
	v_exp_f32_e32 v64, v64
	v_exp_f32_e32 v65, v65
	v_exp_f32_e32 v66, v66
	v_exp_f32_e32 v67, v67
	v_exp_f32_e32 v68, v68
	v_exp_f32_e32 v69, v69
	v_exp_f32_e32 v70, v70
	v_exp_f32_e32 v71, v71
	v_pk_fma_f32 v[64:65], v[64:65], s[98:99], s[98:99]
	v_pk_fma_f32 v[66:67], v[66:67], s[98:99], s[98:99]
	v_pk_fma_f32 v[68:69], v[68:69], s[98:99], s[98:99]
	v_pk_fma_f32 v[70:71], v[70:71], s[98:99], s[98:99]
	v_rcp_f32_e32 v64, v64
	v_rcp_f32_e32 v65, v65
	v_pk_mul_f32 v[40:41], v[40:41], v[44:45]
	v_rcp_f32_e32 v66, v66
	v_rcp_f32_e32 v67, v67
	v_pk_mul_f32 v[42:43], v[42:43], v[46:47]
	v_rcp_f32_e32 v68, v68
	v_rcp_f32_e32 v69, v69
	v_pk_mul_f32 v[32:33], v[32:33], v[36:37]
	v_rcp_f32_e32 v70, v70
	v_rcp_f32_e32 v71, v71
	v_pk_mul_f32 v[34:35], v[34:35], v[38:39]
	v_pk_mul_f32 v[40:41], v[40:41], v[64:65]
	v_pk_mul_f32 v[42:43], v[42:43], v[66:67]
	v_pk_mul_f32 v[32:33], v[32:33], v[68:69]
	v_pk_mul_f32 v[34:35], v[34:35], v[70:71]
	v_med3_f32 v40, v40, s68, v150
	v_med3_f32 v41, v41, s68, v150
	v_med3_f32 v42, v42, s68, v150
	v_med3_f32 v43, v43, s68, v150
	v_med3_f32 v32, v32, s68, v150
	v_med3_f32 v33, v33, s68, v150
	v_med3_f32 v34, v34, s68, v150
	v_med3_f32 v35, v35, s68, v150
	v_cvt_pk_fp8_f32 v140, v40, v41
	v_cvt_pk_fp8_f32 v141, v32, v33
	v_cvt_pk_fp8_f32 v140, v42, v43 op_sel:[0,0,1]
	v_cvt_pk_fp8_f32 v141, v34, v35 op_sel:[0,0,1]
	s_nop 0
	ds_bpermute_b32 v118, v125, v140
	ds_bpermute_b32 v119, v125, v141
	s_waitcnt lgkmcnt(2)
	s_add_u32 s100, s26, 0x40000
	s_addc_u32 s101, s27, 0
	global_store_dwordx2 v124, v[126:127], s[100:101]
	v_pk_mul_f32 v[64:65], v[24:25], s[10:11] op_sel_hi:[1,0]
	v_pk_mul_f32 v[66:67], v[26:27], s[10:11] op_sel_hi:[1,0]
	v_pk_mul_f32 v[68:69], v[234:235], s[10:11] op_sel_hi:[1,0]
	v_pk_mul_f32 v[70:71], v[236:237], s[10:11] op_sel_hi:[1,0]
	v_exp_f32_e32 v64, v64
	v_exp_f32_e32 v65, v65
	v_exp_f32_e32 v66, v66
	v_exp_f32_e32 v67, v67
	v_exp_f32_e32 v68, v68
	v_exp_f32_e32 v69, v69
	v_exp_f32_e32 v70, v70
	v_exp_f32_e32 v71, v71
	v_pk_fma_f32 v[64:65], v[64:65], s[98:99], s[98:99]
	v_pk_fma_f32 v[66:67], v[66:67], s[98:99], s[98:99]
	v_pk_fma_f32 v[68:69], v[68:69], s[98:99], s[98:99]
	v_pk_fma_f32 v[70:71], v[70:71], s[98:99], s[98:99]
	v_rcp_f32_e32 v64, v64
	v_rcp_f32_e32 v65, v65
	v_pk_mul_f32 v[24:25], v[24:25], v[28:29]
	v_rcp_f32_e32 v66, v66
	v_rcp_f32_e32 v67, v67
	v_pk_mul_f32 v[26:27], v[26:27], v[30:31]
	v_rcp_f32_e32 v68, v68
	v_rcp_f32_e32 v69, v69
	v_pk_mul_f32 v[234:235], v[234:235], v[16:17]
	v_rcp_f32_e32 v70, v70
	v_rcp_f32_e32 v71, v71
	v_pk_mul_f32 v[236:237], v[236:237], v[18:19]
	v_pk_mul_f32 v[24:25], v[24:25], v[64:65]
	v_pk_mul_f32 v[26:27], v[26:27], v[66:67]
	v_pk_mul_f32 v[234:235], v[234:235], v[68:69]
	v_pk_mul_f32 v[236:237], v[236:237], v[70:71]
	v_med3_f32 v24, v24, s68, v150
	v_med3_f32 v25, v25, s68, v150
	v_med3_f32 v26, v26, s68, v150
	v_med3_f32 v27, v27, s68, v150
	v_med3_f32 v234, v234, s68, v150
	v_med3_f32 v235, v235, s68, v150
	v_med3_f32 v236, v236, s68, v150
	v_med3_f32 v237, v237, s68, v150
	v_cvt_pk_fp8_f32 v136, v24, v25
	v_cvt_pk_fp8_f32 v137, v234, v235
	v_cvt_pk_fp8_f32 v136, v26, v27 op_sel:[0,0,1]
	v_cvt_pk_fp8_f32 v137, v236, v237 op_sel:[0,0,1]
	s_nop 0
	ds_bpermute_b32 v126, v125, v136
	ds_bpermute_b32 v127, v125, v137
	s_waitcnt lgkmcnt(2)
	s_add_u32 s100, s26, 0x48000
	s_addc_u32 s101, s27, 0
	global_store_dwordx2 v124, v[118:119], s[100:101]
	v_pk_mul_f32 v[64:65], v[8:9], s[10:11] op_sel_hi:[1,0]
	v_pk_mul_f32 v[66:67], v[10:11], s[10:11] op_sel_hi:[1,0]
	v_pk_mul_f32 v[68:69], v[0:1], s[10:11] op_sel_hi:[1,0]
	v_pk_mul_f32 v[70:71], v[2:3], s[10:11] op_sel_hi:[1,0]
	v_exp_f32_e32 v64, v64
	v_exp_f32_e32 v65, v65
	v_exp_f32_e32 v66, v66
	v_exp_f32_e32 v67, v67
	v_exp_f32_e32 v68, v68
	v_exp_f32_e32 v69, v69
	v_exp_f32_e32 v70, v70
	v_exp_f32_e32 v71, v71
	v_pk_fma_f32 v[64:65], v[64:65], s[98:99], s[98:99]
	v_pk_fma_f32 v[66:67], v[66:67], s[98:99], s[98:99]
	v_pk_fma_f32 v[68:69], v[68:69], s[98:99], s[98:99]
	v_pk_fma_f32 v[70:71], v[70:71], s[98:99], s[98:99]
	v_rcp_f32_e32 v64, v64
	v_rcp_f32_e32 v65, v65
	v_pk_mul_f32 v[8:9], v[8:9], v[12:13]
	v_rcp_f32_e32 v66, v66
	v_rcp_f32_e32 v67, v67
	v_pk_mul_f32 v[10:11], v[10:11], v[14:15]
	v_rcp_f32_e32 v68, v68
	v_rcp_f32_e32 v69, v69
	v_pk_mul_f32 v[0:1], v[0:1], v[4:5]
	v_rcp_f32_e32 v70, v70
	v_rcp_f32_e32 v71, v71
	v_pk_mul_f32 v[2:3], v[2:3], v[6:7]
	v_pk_mul_f32 v[8:9], v[8:9], v[64:65]
	v_pk_mul_f32 v[10:11], v[10:11], v[66:67]
	v_pk_mul_f32 v[0:1], v[0:1], v[68:69]
	v_pk_mul_f32 v[2:3], v[2:3], v[70:71]
	v_med3_f32 v8, v8, s68, v150
	v_med3_f32 v9, v9, s68, v150
	v_med3_f32 v10, v10, s68, v150
	v_med3_f32 v11, v11, s68, v150
	v_med3_f32 v0, v0, s68, v150
	v_med3_f32 v1, v1, s68, v150
	v_med3_f32 v2, v2, s68, v150
	v_med3_f32 v3, v3, s68, v150
	v_cvt_pk_fp8_f32 v140, v8, v9
	v_cvt_pk_fp8_f32 v141, v0, v1
	v_cvt_pk_fp8_f32 v140, v10, v11 op_sel:[0,0,1]
	v_cvt_pk_fp8_f32 v141, v2, v3 op_sel:[0,0,1]
	s_nop 0
	ds_bpermute_b32 v118, v125, v140
	ds_bpermute_b32 v119, v125, v141
	s_waitcnt lgkmcnt(2)
	s_add_u32 s100, s26, 0x50000
	s_addc_u32 s101, s27, 0
	global_store_dwordx2 v124, v[126:127], s[100:101]
	s_waitcnt lgkmcnt(0)
	s_add_u32 s100, s26, 0x58000
	s_addc_u32 s101, s27, 0
	global_store_dwordx2 v124, v[118:119], s[100:101]
	s_andn2_b64 vcc, exec, s[4:5]
	s_cbranch_vccnz .LBB0_964
	v_mov_b32_e32 v4, s72
	ds_read_b128 v[120:123], v4
	ds_read_b128 v[112:115], v4
	ds_read_b128 v[104:107], v4
	ds_read_b128 v[96:99], v4
	ds_read_b128 v[88:91], v4
	ds_read_b128 v[80:83], v4
	ds_read_b128 v[72:75], v4
	ds_read_b128 v[230:233], v4
	ds_read_b128 v[124:127], v4
	ds_read_b128 v[116:119], v4
	ds_read_b128 v[108:111], v4
	ds_read_b128 v[100:103], v4
	ds_read_b128 v[92:95], v4
	ds_read_b128 v[84:87], v4
	ds_read_b128 v[76:79], v4
	ds_read_b128 v[20:23], v4
	ds_read_b128 v[56:59], v4
	ds_read_b128 v[48:51], v4
	ds_read_b128 v[40:43], v4
	ds_read_b128 v[32:35], v4
	ds_read_b128 v[24:27], v4
	ds_read_b128 v[234:237], v4
	ds_read_b128 v[8:11], v4
	ds_read_b128 v[0:3], v4
	ds_read_b128 v[60:63], v4
	ds_read_b128 v[52:55], v4
	ds_read_b128 v[44:47], v4
	ds_read_b128 v[36:39], v4
	ds_read_b128 v[28:31], v4
	ds_read_b128 v[16:19], v4
	ds_read_b128 v[12:15], v4
	ds_read_b128 v[4:7], v4
	ds_read2st64_b32 v[142:143], v143 offset1:2
	ds_read2st64_b32 v[144:145], v145 offset1:2
	s_andn2_b64 vcc, exec, s[14:15]
	s_cbranch_vccnz .LBB0_953
	s_barrier
	s_branch .LBB0_953

.LBB0_1875:
	s_ashr_i32 s27, s26, 31
	s_lshl_b64 s[26:27], s[26:27], 19
	s_add_u32 s21, s56, s26
	s_addc_u32 s30, s57, s27
	s_ashr_i32 s29, s28, 31
	s_lshl_b64 s[26:27], s[28:29], 7
	s_add_u32 s21, s21, s26
	s_addc_u32 s27, s30, s27
	s_add_u32 s26, s21, s58
	s_addc_u32 s27, s27, 0
	s_mov_b32 s98, 0x44800000
	s_mov_b32 s99, 0x44800000
	v_pk_mul_f32 v[64:65], v[120:121], s[10:11] op_sel_hi:[1,0]
	v_pk_mul_f32 v[66:67], v[122:123], s[10:11] op_sel_hi:[1,0]
	v_pk_mul_f32 v[68:69], v[112:113], s[10:11] op_sel_hi:[1,0]
	v_pk_mul_f32 v[70:71], v[114:115], s[10:11] op_sel_hi:[1,0]
	v_exp_f32_e32 v64, v64
	v_exp_f32_e32 v65, v65
	v_exp_f32_e32 v66, v66
	v_exp_f32_e32 v67, v67
	v_exp_f32_e32 v68, v68
	v_exp_f32_e32 v69, v69
	v_exp_f32_e32 v70, v70
	v_exp_f32_e32 v71, v71
	v_pk_fma_f32 v[64:65], v[64:65], s[98:99], s[98:99]
	v_pk_fma_f32 v[66:67], v[66:67], s[98:99], s[98:99]
	v_pk_fma_f32 v[68:69], v[68:69], s[98:99], s[98:99]
	v_pk_fma_f32 v[70:71], v[70:71], s[98:99], s[98:99]
	v_rcp_f32_e32 v64, v64
	v_rcp_f32_e32 v65, v65
	v_pk_mul_f32 v[120:121], v[120:121], v[124:125]
	v_rcp_f32_e32 v66, v66
	v_rcp_f32_e32 v67, v67
	v_pk_mul_f32 v[122:123], v[122:123], v[126:127]
	v_rcp_f32_e32 v68, v68
	v_rcp_f32_e32 v69, v69
	v_pk_mul_f32 v[112:113], v[112:113], v[116:117]
	v_rcp_f32_e32 v70, v70
	v_rcp_f32_e32 v71, v71
	v_pk_mul_f32 v[114:115], v[114:115], v[118:119]
	v_mbcnt_lo_u32_b32 v136, -1, 0
	v_mbcnt_hi_u32_b32 v136, -1, v136
	v_lshrrev_b32_e32 v137, 2, v136
	v_and_b32_e32 v124, 15, v136
	v_sub_u32_e32 v124, v137, v124
	v_lshlrev_b32_e32 v124, 11, v124
	v_and_b32_e32 v136, 3, v136
	v_lshl_add_u32 v124, v136, 3, v124
	v_add_u32_e32 v124, v134, v124
	v_lshl_add_u32 v125, v136, 4, v137
	v_lshlrev_b32_e32 v125, 2, v125
	v_pk_mul_f32 v[120:121], v[120:121], v[64:65]
	v_pk_mul_f32 v[122:123], v[122:123], v[66:67]
	v_pk_mul_f32 v[112:113], v[112:113], v[68:69]
	v_pk_mul_f32 v[114:115], v[114:115], v[70:71]
	v_med3_f32 v120, v120, s67, v150
	v_med3_f32 v121, v121, s67, v150
	v_med3_f32 v122, v122, s67, v150
	v_med3_f32 v123, v123, s67, v150
	v_med3_f32 v112, v112, s67, v150
	v_med3_f32 v113, v113, s67, v150
	v_med3_f32 v114, v114, s67, v150
	v_med3_f32 v115, v115, s67, v150
	v_cvt_pk_fp8_f32 v136, v120, v121
	v_cvt_pk_fp8_f32 v137, v112, v113
	v_cvt_pk_fp8_f32 v136, v122, v123 op_sel:[0,0,1]
	v_cvt_pk_fp8_f32 v137, v114, v115 op_sel:[0,0,1]
	s_nop 0
	ds_bpermute_b32 v126, v125, v136
	ds_bpermute_b32 v127, v125, v137
	v_pk_mul_f32 v[64:65], v[104:105], s[10:11] op_sel_hi:[1,0]
	v_pk_mul_f32 v[66:67], v[106:107], s[10:11] op_sel_hi:[1,0]
	v_pk_mul_f32 v[68:69], v[96:97], s[10:11] op_sel_hi:[1,0]
	v_pk_mul_f32 v[70:71], v[98:99], s[10:11] op_sel_hi:[1,0]
	v_exp_f32_e32 v64, v64
	v_exp_f32_e32 v65, v65
	v_exp_f32_e32 v66, v66
	v_exp_f32_e32 v67, v67
	v_exp_f32_e32 v68, v68
	v_exp_f32_e32 v69, v69
	v_exp_f32_e32 v70, v70
	v_exp_f32_e32 v71, v71
	v_pk_fma_f32 v[64:65], v[64:65], s[98:99], s[98:99]
	v_pk_fma_f32 v[66:67], v[66:67], s[98:99], s[98:99]
	v_pk_fma_f32 v[68:69], v[68:69], s[98:99], s[98:99]
	v_pk_fma_f32 v[70:71], v[70:71], s[98:99], s[98:99]
	v_rcp_f32_e32 v64, v64
	v_rcp_f32_e32 v65, v65
	v_pk_mul_f32 v[104:105], v[104:105], v[108:109]
	v_rcp_f32_e32 v66, v66
	v_rcp_f32_e32 v67, v67
	v_pk_mul_f32 v[106:107], v[106:107], v[110:111]
	v_rcp_f32_e32 v68, v68
	v_rcp_f32_e32 v69, v69
	v_pk_mul_f32 v[96:97], v[96:97], v[100:101]
	v_rcp_f32_e32 v70, v70
	v_rcp_f32_e32 v71, v71
	v_pk_mul_f32 v[98:99], v[98:99], v[102:103]
	v_pk_mul_f32 v[104:105], v[104:105], v[64:65]
	v_pk_mul_f32 v[106:107], v[106:107], v[66:67]
	v_pk_mul_f32 v[96:97], v[96:97], v[68:69]
	v_pk_mul_f32 v[98:99], v[98:99], v[70:71]
	v_med3_f32 v104, v104, s67, v150
	v_med3_f32 v105, v105, s67, v150
	v_med3_f32 v106, v106, s67, v150
	v_med3_f32 v107, v107, s67, v150
	v_med3_f32 v96, v96, s67, v150
	v_med3_f32 v97, v97, s67, v150
	v_med3_f32 v98, v98, s67, v150
	v_med3_f32 v99, v99, s67, v150
	v_cvt_pk_fp8_f32 v140, v104, v105
	v_cvt_pk_fp8_f32 v141, v96, v97
	v_cvt_pk_fp8_f32 v140, v106, v107 op_sel:[0,0,1]
	v_cvt_pk_fp8_f32 v141, v98, v99 op_sel:[0,0,1]
	s_nop 0
	ds_bpermute_b32 v118, v125, v140
	ds_bpermute_b32 v119, v125, v141
	s_waitcnt lgkmcnt(2)
	s_mov_b32 s100, s26
	s_mov_b32 s101, s27
	global_store_dwordx2 v124, v[126:127], s[100:101]
	v_pk_mul_f32 v[64:65], v[88:89], s[10:11] op_sel_hi:[1,0]
	v_pk_mul_f32 v[66:67], v[90:91], s[10:11] op_sel_hi:[1,0]
	v_pk_mul_f32 v[68:69], v[80:81], s[10:11] op_sel_hi:[1,0]
	v_pk_mul_f32 v[70:71], v[82:83], s[10:11] op_sel_hi:[1,0]
	v_exp_f32_e32 v64, v64
	v_exp_f32_e32 v65, v65
	v_exp_f32_e32 v66, v66
	v_exp_f32_e32 v67, v67
	v_exp_f32_e32 v68, v68
	v_exp_f32_e32 v69, v69
	v_exp_f32_e32 v70, v70
	v_exp_f32_e32 v71, v71
	v_pk_fma_f32 v[64:65], v[64:65], s[98:99], s[98:99]
	v_pk_fma_f32 v[66:67], v[66:67], s[98:99], s[98:99]
	v_pk_fma_f32 v[68:69], v[68:69], s[98:99], s[98:99]
	v_pk_fma_f32 v[70:71], v[70:71], s[98:99], s[98:99]
	v_rcp_f32_e32 v64, v64
	v_rcp_f32_e32 v65, v65
	v_pk_mul_f32 v[88:89], v[88:89], v[92:93]
	v_rcp_f32_e32 v66, v66
	v_rcp_f32_e32 v67, v67
	v_pk_mul_f32 v[90:91], v[90:91], v[94:95]
	v_rcp_f32_e32 v68, v68
	v_rcp_f32_e32 v69, v69
	v_pk_mul_f32 v[80:81], v[80:81], v[84:85]
	v_rcp_f32_e32 v70, v70
	v_rcp_f32_e32 v71, v71
	v_pk_mul_f32 v[82:83], v[82:83], v[86:87]
	v_pk_mul_f32 v[88:89], v[88:89], v[64:65]
	v_pk_mul_f32 v[90:91], v[90:91], v[66:67]
	v_pk_mul_f32 v[80:81], v[80:81], v[68:69]
	v_pk_mul_f32 v[82:83], v[82:83], v[70:71]
	v_med3_f32 v88, v88, s67, v150
	v_med3_f32 v89, v89, s67, v150
	v_med3_f32 v90, v90, s67, v150
	v_med3_f32 v91, v91, s67, v150
	v_med3_f32 v80, v80, s67, v150
	v_med3_f32 v81, v81, s67, v150
	v_med3_f32 v82, v82, s67, v150
	v_med3_f32 v83, v83, s67, v150
	v_cvt_pk_fp8_f32 v136, v88, v89
	v_cvt_pk_fp8_f32 v137, v80, v81
	v_cvt_pk_fp8_f32 v136, v90, v91 op_sel:[0,0,1]
	v_cvt_pk_fp8_f32 v137, v82, v83 op_sel:[0,0,1]
	s_nop 0
	ds_bpermute_b32 v126, v125, v136
	ds_bpermute_b32 v127, v125, v137
	s_waitcnt lgkmcnt(2)
	s_add_u32 s100, s26, 0x8000
	s_addc_u32 s101, s27, 0
	global_store_dwordx2 v124, v[118:119], s[100:101]
	v_pk_mul_f32 v[64:65], v[72:73], s[10:11] op_sel_hi:[1,0]
	v_pk_mul_f32 v[66:67], v[74:75], s[10:11] op_sel_hi:[1,0]
	v_pk_mul_f32 v[68:69], v[230:231], s[10:11] op_sel_hi:[1,0]
	v_pk_mul_f32 v[70:71], v[232:233], s[10:11] op_sel_hi:[1,0]
	v_exp_f32_e32 v64, v64
	v_exp_f32_e32 v65, v65
	v_exp_f32_e32 v66, v66
	v_exp_f32_e32 v67, v67
	v_exp_f32_e32 v68, v68
	v_exp_f32_e32 v69, v69
	v_exp_f32_e32 v70, v70
	v_exp_f32_e32 v71, v71
	v_pk_fma_f32 v[64:65], v[64:65], s[98:99], s[98:99]
	v_pk_fma_f32 v[66:67], v[66:67], s[98:99], s[98:99]
	v_pk_fma_f32 v[68:69], v[68:69], s[98:99], s[98:99]
	v_pk_fma_f32 v[70:71], v[70:71], s[98:99], s[98:99]
	v_rcp_f32_e32 v64, v64
	v_rcp_f32_e32 v65, v65
	v_pk_mul_f32 v[72:73], v[72:73], v[76:77]
	v_rcp_f32_e32 v66, v66
	v_rcp_f32_e32 v67, v67
	v_pk_mul_f32 v[74:75], v[74:75], v[78:79]
	v_rcp_f32_e32 v68, v68
	v_rcp_f32_e32 v69, v69
	v_pk_mul_f32 v[230:231], v[230:231], v[20:21]
	v_rcp_f32_e32 v70, v70
	v_rcp_f32_e32 v71, v71
	v_pk_mul_f32 v[232:233], v[232:233], v[22:23]
	v_pk_mul_f32 v[72:73], v[72:73], v[64:65]
	v_pk_mul_f32 v[74:75], v[74:75], v[66:67]
	v_pk_mul_f32 v[230:231], v[230:231], v[68:69]
	v_pk_mul_f32 v[232:233], v[232:233], v[70:71]
	v_med3_f32 v72, v72, s67, v150
	v_med3_f32 v73, v73, s67, v150
	v_med3_f32 v74, v74, s67, v150
	v_med3_f32 v75, v75, s67, v150
	v_med3_f32 v230, v230, s67, v150
	v_med3_f32 v231, v231, s67, v150
	v_med3_f32 v232, v232, s67, v150
	v_med3_f32 v233, v233, s67, v150
	v_cvt_pk_fp8_f32 v140, v72, v73
	v_cvt_pk_fp8_f32 v141, v230, v231
	v_cvt_pk_fp8_f32 v140, v74, v75 op_sel:[0,0,1]
	v_cvt_pk_fp8_f32 v141, v232, v233 op_sel:[0,0,1]
	s_nop 0
	ds_bpermute_b32 v118, v125, v140
	ds_bpermute_b32 v119, v125, v141
	s_waitcnt lgkmcnt(2)
	s_add_u32 s100, s26, 0x10000
	s_addc_u32 s101, s27, 0
	global_store_dwordx2 v124, v[126:127], s[100:101]
	v_pk_mul_f32 v[64:65], v[56:57], s[10:11] op_sel_hi:[1,0]
	v_pk_mul_f32 v[66:67], v[58:59], s[10:11] op_sel_hi:[1,0]
	v_pk_mul_f32 v[68:69], v[48:49], s[10:11] op_sel_hi:[1,0]
	v_pk_mul_f32 v[70:71], v[50:51], s[10:11] op_sel_hi:[1,0]
	v_exp_f32_e32 v64, v64
	v_exp_f32_e32 v65, v65
	v_exp_f32_e32 v66, v66
	v_exp_f32_e32 v67, v67
	v_exp_f32_e32 v68, v68
	v_exp_f32_e32 v69, v69
	v_exp_f32_e32 v70, v70
	v_exp_f32_e32 v71, v71
	v_pk_fma_f32 v[64:65], v[64:65], s[98:99], s[98:99]
	v_pk_fma_f32 v[66:67], v[66:67], s[98:99], s[98:99]
	v_pk_fma_f32 v[68:69], v[68:69], s[98:99], s[98:99]
	v_pk_fma_f32 v[70:71], v[70:71], s[98:99], s[98:99]
	v_rcp_f32_e32 v64, v64
	v_rcp_f32_e32 v65, v65
	v_pk_mul_f32 v[56:57], v[56:57], v[60:61]
	v_rcp_f32_e32 v66, v66
	v_rcp_f32_e32 v67, v67
	v_pk_mul_f32 v[58:59], v[58:59], v[62:63]
	v_rcp_f32_e32 v68, v68
	v_rcp_f32_e32 v69, v69
	v_pk_mul_f32 v[48:49], v[48:49], v[52:53]
	v_rcp_f32_e32 v70, v70
	v_rcp_f32_e32 v71, v71
	v_pk_mul_f32 v[50:51], v[50:51], v[54:55]
	v_pk_mul_f32 v[56:57], v[56:57], v[64:65]
	v_pk_mul_f32 v[58:59], v[58:59], v[66:67]
	v_pk_mul_f32 v[48:49], v[48:49], v[68:69]
	v_pk_mul_f32 v[50:51], v[50:51], v[70:71]
	v_med3_f32 v56, v56, s67, v150
	v_med3_f32 v57, v57, s67, v150
	v_med3_f32 v58, v58, s67, v150
	v_med3_f32 v59, v59, s67, v150
	v_med3_f32 v48, v48, s67, v150
	v_med3_f32 v49, v49, s67, v150
	v_med3_f32 v50, v50, s67, v150
	v_med3_f32 v51, v51, s67, v150
	v_cvt_pk_fp8_f32 v136, v56, v57
	v_cvt_pk_fp8_f32 v137, v48, v49
	v_cvt_pk_fp8_f32 v136, v58, v59 op_sel:[0,0,1]
	v_cvt_pk_fp8_f32 v137, v50, v51 op_sel:[0,0,1]
	s_nop 0
	ds_bpermute_b32 v126, v125, v136
	ds_bpermute_b32 v127, v125, v137
	s_waitcnt lgkmcnt(2)
	s_add_u32 s100, s26, 0x18000
	s_addc_u32 s101, s27, 0
	global_store_dwordx2 v124, v[118:119], s[100:101]
	v_pk_mul_f32 v[64:65], v[40:41], s[10:11] op_sel_hi:[1,0]
	v_pk_mul_f32 v[66:67], v[42:43], s[10:11] op_sel_hi:[1,0]
	v_pk_mul_f32 v[68:69], v[32:33], s[10:11] op_sel_hi:[1,0]
	v_pk_mul_f32 v[70:71], v[34:35], s[10:11] op_sel_hi:[1,0]
	v_exp_f32_e32 v64, v64
	v_exp_f32_e32 v65, v65
	v_exp_f32_e32 v66, v66
	v_exp_f32_e32 v67, v67
	v_exp_f32_e32 v68, v68
	v_exp_f32_e32 v69, v69
	v_exp_f32_e32 v70, v70
	v_exp_f32_e32 v71, v71
	v_pk_fma_f32 v[64:65], v[64:65], s[98:99], s[98:99]
	v_pk_fma_f32 v[66:67], v[66:67], s[98:99], s[98:99]
	v_pk_fma_f32 v[68:69], v[68:69], s[98:99], s[98:99]
	v_pk_fma_f32 v[70:71], v[70:71], s[98:99], s[98:99]
	v_rcp_f32_e32 v64, v64
	v_rcp_f32_e32 v65, v65
	v_pk_mul_f32 v[40:41], v[40:41], v[44:45]
	v_rcp_f32_e32 v66, v66
	v_rcp_f32_e32 v67, v67
	v_pk_mul_f32 v[42:43], v[42:43], v[46:47]
	v_rcp_f32_e32 v68, v68
	v_rcp_f32_e32 v69, v69
	v_pk_mul_f32 v[32:33], v[32:33], v[36:37]
	v_rcp_f32_e32 v70, v70
	v_rcp_f32_e32 v71, v71
	v_pk_mul_f32 v[34:35], v[34:35], v[38:39]
	v_pk_mul_f32 v[40:41], v[40:41], v[64:65]
	v_pk_mul_f32 v[42:43], v[42:43], v[66:67]
	v_pk_mul_f32 v[32:33], v[32:33], v[68:69]
	v_pk_mul_f32 v[34:35], v[34:35], v[70:71]
	v_med3_f32 v40, v40, s67, v150
	v_med3_f32 v41, v41, s67, v150
	v_med3_f32 v42, v42, s67, v150
	v_med3_f32 v43, v43, s67, v150
	v_med3_f32 v32, v32, s67, v150
	v_med3_f32 v33, v33, s67, v150
	v_med3_f32 v34, v34, s67, v150
	v_med3_f32 v35, v35, s67, v150
	v_cvt_pk_fp8_f32 v140, v40, v41
	v_cvt_pk_fp8_f32 v141, v32, v33
	v_cvt_pk_fp8_f32 v140, v42, v43 op_sel:[0,0,1]
	v_cvt_pk_fp8_f32 v141, v34, v35 op_sel:[0,0,1]
	s_nop 0
	ds_bpermute_b32 v118, v125, v140
	ds_bpermute_b32 v119, v125, v141
	s_waitcnt lgkmcnt(2)
	s_add_u32 s100, s26, 0x40000
	s_addc_u32 s101, s27, 0
	global_store_dwordx2 v124, v[126:127], s[100:101]
	v_pk_mul_f32 v[64:65], v[24:25], s[10:11] op_sel_hi:[1,0]
	v_pk_mul_f32 v[66:67], v[26:27], s[10:11] op_sel_hi:[1,0]
	v_pk_mul_f32 v[68:69], v[234:235], s[10:11] op_sel_hi:[1,0]
	v_pk_mul_f32 v[70:71], v[236:237], s[10:11] op_sel_hi:[1,0]
	v_exp_f32_e32 v64, v64
	v_exp_f32_e32 v65, v65
	v_exp_f32_e32 v66, v66
	v_exp_f32_e32 v67, v67
	v_exp_f32_e32 v68, v68
	v_exp_f32_e32 v69, v69
	v_exp_f32_e32 v70, v70
	v_exp_f32_e32 v71, v71
	v_pk_fma_f32 v[64:65], v[64:65], s[98:99], s[98:99]
	v_pk_fma_f32 v[66:67], v[66:67], s[98:99], s[98:99]
	v_pk_fma_f32 v[68:69], v[68:69], s[98:99], s[98:99]
	v_pk_fma_f32 v[70:71], v[70:71], s[98:99], s[98:99]
	v_rcp_f32_e32 v64, v64
	v_rcp_f32_e32 v65, v65
	v_pk_mul_f32 v[24:25], v[24:25], v[28:29]
	v_rcp_f32_e32 v66, v66
	v_rcp_f32_e32 v67, v67
	v_pk_mul_f32 v[26:27], v[26:27], v[30:31]
	v_rcp_f32_e32 v68, v68
	v_rcp_f32_e32 v69, v69
	v_pk_mul_f32 v[234:235], v[234:235], v[16:17]
	v_rcp_f32_e32 v70, v70
	v_rcp_f32_e32 v71, v71
	v_pk_mul_f32 v[236:237], v[236:237], v[18:19]
	v_pk_mul_f32 v[24:25], v[24:25], v[64:65]
	v_pk_mul_f32 v[26:27], v[26:27], v[66:67]
	v_pk_mul_f32 v[234:235], v[234:235], v[68:69]
	v_pk_mul_f32 v[236:237], v[236:237], v[70:71]
	v_med3_f32 v24, v24, s67, v150
	v_med3_f32 v25, v25, s67, v150
	v_med3_f32 v26, v26, s67, v150
	v_med3_f32 v27, v27, s67, v150
	v_med3_f32 v234, v234, s67, v150
	v_med3_f32 v235, v235, s67, v150
	v_med3_f32 v236, v236, s67, v150
	v_med3_f32 v237, v237, s67, v150
	v_cvt_pk_fp8_f32 v136, v24, v25
	v_cvt_pk_fp8_f32 v137, v234, v235
	v_cvt_pk_fp8_f32 v136, v26, v27 op_sel:[0,0,1]
	v_cvt_pk_fp8_f32 v137, v236, v237 op_sel:[0,0,1]
	s_nop 0
	ds_bpermute_b32 v126, v125, v136
	ds_bpermute_b32 v127, v125, v137
	s_waitcnt lgkmcnt(2)
	s_add_u32 s100, s26, 0x48000
	s_addc_u32 s101, s27, 0
	global_store_dwordx2 v124, v[118:119], s[100:101]
	v_pk_mul_f32 v[64:65], v[8:9], s[10:11] op_sel_hi:[1,0]
	v_pk_mul_f32 v[66:67], v[10:11], s[10:11] op_sel_hi:[1,0]
	v_pk_mul_f32 v[68:69], v[0:1], s[10:11] op_sel_hi:[1,0]
	v_pk_mul_f32 v[70:71], v[2:3], s[10:11] op_sel_hi:[1,0]
	v_exp_f32_e32 v64, v64
	v_exp_f32_e32 v65, v65
	v_exp_f32_e32 v66, v66
	v_exp_f32_e32 v67, v67
	v_exp_f32_e32 v68, v68
	v_exp_f32_e32 v69, v69
	v_exp_f32_e32 v70, v70
	v_exp_f32_e32 v71, v71
	v_pk_fma_f32 v[64:65], v[64:65], s[98:99], s[98:99]
	v_pk_fma_f32 v[66:67], v[66:67], s[98:99], s[98:99]
	v_pk_fma_f32 v[68:69], v[68:69], s[98:99], s[98:99]
	v_pk_fma_f32 v[70:71], v[70:71], s[98:99], s[98:99]
	v_rcp_f32_e32 v64, v64
	v_rcp_f32_e32 v65, v65
	v_pk_mul_f32 v[8:9], v[8:9], v[12:13]
	v_rcp_f32_e32 v66, v66
	v_rcp_f32_e32 v67, v67
	v_pk_mul_f32 v[10:11], v[10:11], v[14:15]
	v_rcp_f32_e32 v68, v68
	v_rcp_f32_e32 v69, v69
	v_pk_mul_f32 v[0:1], v[0:1], v[4:5]
	v_rcp_f32_e32 v70, v70
	v_rcp_f32_e32 v71, v71
	v_pk_mul_f32 v[2:3], v[2:3], v[6:7]
	v_pk_mul_f32 v[8:9], v[8:9], v[64:65]
	v_pk_mul_f32 v[10:11], v[10:11], v[66:67]
	v_pk_mul_f32 v[0:1], v[0:1], v[68:69]
	v_pk_mul_f32 v[2:3], v[2:3], v[70:71]
	v_med3_f32 v8, v8, s67, v150
	v_med3_f32 v9, v9, s67, v150
	v_med3_f32 v10, v10, s67, v150
	v_med3_f32 v11, v11, s67, v150
	v_med3_f32 v0, v0, s67, v150
	v_med3_f32 v1, v1, s67, v150
	v_med3_f32 v2, v2, s67, v150
	v_med3_f32 v3, v3, s67, v150
	v_cvt_pk_fp8_f32 v140, v8, v9
	v_cvt_pk_fp8_f32 v141, v0, v1
	v_cvt_pk_fp8_f32 v140, v10, v11 op_sel:[0,0,1]
	v_cvt_pk_fp8_f32 v141, v2, v3 op_sel:[0,0,1]
	s_nop 0
	ds_bpermute_b32 v118, v125, v140
	ds_bpermute_b32 v119, v125, v141
	s_waitcnt lgkmcnt(2)
	s_add_u32 s100, s26, 0x50000
	s_addc_u32 s101, s27, 0
	global_store_dwordx2 v124, v[126:127], s[100:101]
	s_waitcnt lgkmcnt(0)
	s_add_u32 s100, s26, 0x58000
	s_addc_u32 s101, s27, 0
	global_store_dwordx2 v124, v[118:119], s[100:101]
	s_andn2_b64 vcc, exec, s[4:5]
	s_cbranch_vccnz .LBB0_1878
	v_mov_b32_e32 v4, s71
	ds_read_b128 v[120:123], v4
	ds_read_b128 v[112:115], v4
	ds_read_b128 v[104:107], v4
	ds_read_b128 v[96:99], v4
	ds_read_b128 v[88:91], v4
	ds_read_b128 v[80:83], v4
	ds_read_b128 v[72:75], v4
	ds_read_b128 v[230:233], v4
	ds_read_b128 v[124:127], v4
	ds_read_b128 v[116:119], v4
	ds_read_b128 v[108:111], v4
	ds_read_b128 v[100:103], v4
	ds_read_b128 v[92:95], v4
	ds_read_b128 v[84:87], v4
	ds_read_b128 v[76:79], v4
	ds_read_b128 v[20:23], v4
	ds_read_b128 v[56:59], v4
	ds_read_b128 v[48:51], v4
	ds_read_b128 v[40:43], v4
	ds_read_b128 v[32:35], v4
	ds_read_b128 v[24:27], v4
	ds_read_b128 v[234:237], v4
	ds_read_b128 v[8:11], v4
	ds_read_b128 v[0:3], v4
	ds_read_b128 v[60:63], v4
	ds_read_b128 v[52:55], v4
	ds_read_b128 v[44:47], v4
	ds_read_b128 v[36:39], v4
	ds_read_b128 v[28:31], v4
	ds_read_b128 v[16:19], v4
	ds_read_b128 v[12:15], v4
	ds_read_b128 v[4:7], v4
	ds_read2st64_b32 v[142:143], v143 offset1:2
	ds_read2st64_b32 v[144:145], v145 offset1:2
	s_andn2_b64 vcc, exec, s[14:15]
	s_cbranch_vccnz .LBB0_1867
	s_barrier
	s_branch .LBB0_1867
